# P0 tail rebalance: the small-parameter conversion (load->store chain) is done by the last 7 workgroups, which have no rope/zeroing work, instead of the first 7 (on v81)
# baseline (speedup 1.0000x reference)
; __global__ void __launch_bounds__(NT, 2) fwd_mega(Args A) {
;     ...
;         const int gt = vcu * NT + tid, NGT = G * NT;
;     ...
;         for (int i = gt; i < PAR_N; i += NGT) {
;             float v = 0.f;
;             if (i < PAR_GK) v = A.g_q[i]; else if (i < PAR_SINK) v = A.g_k[i - PAR_GK]; else if (i < PAR_SINK + 8) v = A.sink[i - PAR_SINK];
;             else if (i < PAR_GV) v = 0.f; else if (i < PAR_BV) v = A.g_v_ln[i - PAR_GV]; else if (i < PAR_BSP) v = A.b_v_ln[i - PAR_BV]; else v = A.b_sp[i - PAR_BSP];
;             ((float*)(ws + WS_PAR))[i] = v;
;         }
.LBB0_75:
	s_or_b64 exec, exec, s[4:5]
	v_readlane_b32 s88, v255, 1
	s_movk_i32 s0, 0xe00
	v_readlane_b32 s89, v255, 2
	v_add_u32_e32 v12, 0xfffe0e00, v0
	v_cmp_gt_u32_e32 vcc, s0, v12
	s_and_saveexec_b64 s[4:5], vcc
	s_cbranch_execz .LBB0_100
	s_add_u32 s10, s28, 0x200000
	s_addc_u32 s11, s29, 0
	v_mov_b32_e32 v2, v12
	s_ashr_i32 s7, s6, 31
	v_lshlrev_b64 v[4:5], 2, v[2:3]
	s_lshl_b64 s[36:37], s[6:7], 2
	s_mov_b64 s[38:39], 0
	s_movk_i32 s0, 0x7f
	s_movk_i32 s1, 0xff
	s_movk_i32 s3, 0x107
	s_movk_i32 s7, 0x1ff
	s_movk_i32 s53, 0x5ff
	s_movk_i32 s66, 0x9ff
	v_mov_b32_e32 v7, 0
	s_movk_i32 s67, 0xdff
	v_mov_b32_e32 v6, v12
	s_branch .LBB0_78
